# dn_prep conv loads: 24-bit mad + saddr-form global loads instead of 64-bit mad address chains (12 sites)
# speedup vs baseline: 1.0026x; 1.0026x over previous
; #define LAS __attribute__((address_space(3)))
; __device__ __forceinline__ float lo_bf(unsigned w) { return __uint_as_float(w << 16); }
; __device__ __forceinline__ float hi_bf(unsigned w) { return __uint_as_float(w & 0xffff0000u); }
; __device__ __forceinline__ unsigned pk2(float lo, float hi) { const f32x2_t v = {lo, hi}; const bf16x2_t b = __builtin_convertvector(v, bf16x2_t); return __builtin_bit_cast(unsigned, b); }
; __device__ __forceinline__ float silu_(float x) { return x * sigm(x); }
; __device__ __forceinline__ void dn_prep_item(const Args& a, LAS unsigned char* lds, int item, int tid, int wave, int lane, int& cwh, int next_item) {
;     ...
;     for (int r = 0; r < 6; ++r) { const int task = tid + NTHR * r, which = task >> 10, i = (task & 1023) >> 4, gq = task & 15;
;         const int col = 1024 + which * 512 + h * 128 + 8 * gq;
;         v4u xv[4];
; #pragma unroll
;         for (int jj = 0; jj < 4; ++jj) { const int pos = n * 64 + i - 3 + jj; xv[jj] = (v4u){0u, 0u, 0u, 0u};
;             if (pos >= 0) xv[jj] = *(const v4u*)(P + (size_t)(b * T + pos) * NIN + col); }
;         float o[8];
; #pragma unroll
;         for (int q = 0; q < 8; ++q) o[q] = 0.f;
; #pragma unroll
;         for (int jj = 0; jj < 4; ++jj) { const v4u v = xv[jj];
;             const f32x4 w0 = *(const LAS f32x4*)(cwl + (which * 4 + jj) * 128 + 8 * gq), w1 = *(const LAS f32x4*)(cwl + (which * 4 + jj) * 128 + 8 * gq + 4);
;             o[0] += w0[0] * lo_bf(v.x); o[1] += w0[1] * hi_bf(v.x); o[2] += w0[2] * lo_bf(v.y); o[3] += w0[3] * hi_bf(v.y);
;             o[4] += w1[0] * lo_bf(v.z); o[5] += w1[1] * hi_bf(v.z); o[6] += w1[2] * lo_bf(v.w); o[7] += w1[3] * hi_bf(v.w); }
;         float s = 0.f;
; #pragma unroll
;         for (int q = 0; q < 8; ++q) { o[q] = silu_(o[q]); s += o[q] * o[q]; }
;         s += __shfl_xor(s, 1); s += __shfl_xor(s, 2); s += __shfl_xor(s, 4); s += __shfl_xor(s, 8);
;         const float inv = which == 2 ? 1.0f : rsqrtf(s + EPS) * (which == 0 ? 0.08838834764831845f : 1.0f);
;         v4u w; w.x = pk2(o[0] * inv, o[1] * inv); w.y = pk2(o[2] * inv, o[3] * inv); w.z = pk2(o[4] * inv, o[5] * inv); w.w = pk2(o[6] * inv, o[7] * inv);
;         *(LAS v4u*)(lds + (which == 0 ? L_QS : which == 1 ? L_KH : L_V) + i * KS_ + 16 * gq) = w;
.LBB0_746:
	v_add_u32_e32 v0, s87, v220
	v_lshrrev_b32_e32 v43, 10, v41
	v_and_b32_e32 v42, 63, v0
	v_lshl_add_u32 v1, v43, 9, v36
	v_add_u32_e32 v0, s86, v42
	v_cmp_lt_i32_e32 vcc, -1, v0
	v_mov_b32_e32 v8, 0
	v_lshlrev_b32_e32 v56, 1, v1
	v_mov_b32_e32 v16, 0
	v_mov_b32_e32 v17, 0
	v_mov_b32_e32 v18, 0
	v_mov_b32_e32 v19, 0
	s_and_saveexec_b64 s[22:23], vcc
	s_cbranch_execz .LBB0_748
	v_add_u32_e32 v1, s41, v0
	v_mad_u32_u24 v2, v1, s25, v56
	global_load_dwordx4 v[16:19], v2, s[10:11]
.LBB0_748:
	s_or_b64 exec, exec, s[22:23]
	v_cmp_lt_i32_e32 vcc, -2, v0
	v_mov_b32_e32 v9, 0
	v_mov_b32_e32 v10, 0
	v_mov_b32_e32 v11, 0
	s_and_saveexec_b64 s[22:23], vcc
	s_cbranch_execz .LBB0_750
	v_add_u32_e32 v1, s42, v0
	v_mad_u32_u24 v2, v1, s25, v56
	global_load_dwordx4 v[8:11], v2, s[10:11]
.LBB0_750:
	s_or_b64 exec, exec, s[22:23]
	v_cmp_lt_i32_e32 vcc, -3, v0
	v_mov_b32_e32 v20, 0
	v_mov_b32_e32 v21, 0
	v_mov_b32_e32 v22, 0
	v_mov_b32_e32 v23, 0
	s_and_saveexec_b64 s[22:23], vcc
	s_cbranch_execz .LBB0_752
	v_add_u32_e32 v2, s43, v0
	v_mad_u32_u24 v0, v2, s25, v56
	global_load_dwordx4 v[20:23], v0, s[10:11]
.LBB0_752:
	s_or_b64 exec, exec, s[22:23]
	v_or_b32_e32 v2, s39, v42
	v_mad_u32_u24 v0, v2, s25, v56
	global_load_dwordx4 v[4:7], v0, s[10:11]
	v_lshl_add_u32 v0, v43, 11, v150
	ds_read_b128 v[44:47], v0
	ds_read_b128 v[28:31], v0 offset:16
	ds_read_b128 v[72:75], v0 offset:512
	ds_read_b128 v[24:27], v0 offset:528
	ds_read_b128 v[76:79], v0 offset:1024
	ds_read_b128 v[12:15], v0 offset:1040
	ds_read_b128 v[80:83], v0 offset:1536
	ds_read_b128 v[0:3], v0 offset:1552
	s_waitcnt vmcnt(1)
	v_lshlrev_b32_e32 v32, 16, v16
	v_and_b32_e32 v33, 0xffff0000, v16
	s_waitcnt lgkmcnt(0)
	v_pk_fma_f32 v[32:33], v[44:45], v[32:33], 0 op_sel_hi:[1,1,0]
	v_lshlrev_b32_e32 v34, 16, v8
	v_and_b32_e32 v35, 0xffff0000, v8
	v_pk_fma_f32 v[32:33], v[72:73], v[34:35], v[32:33]
	v_lshlrev_b32_e32 v34, 16, v20
	v_and_b32_e32 v35, 0xffff0000, v20
	v_pk_fma_f32 v[32:33], v[76:77], v[34:35], v[32:33]
	v_lshlrev_b32_e32 v16, 16, v17
	v_and_b32_e32 v17, 0xffff0000, v17
	v_pk_fma_f32 v[16:17], v[46:47], v[16:17], 0 op_sel_hi:[1,1,0]
	v_lshlrev_b32_e32 v20, 16, v18
	v_cmp_ne_u32_e32 vcc, 2, v43
	s_waitcnt vmcnt(0)
	v_lshlrev_b32_e32 v34, 16, v4
	v_and_b32_e32 v35, 0xffff0000, v4
	v_pk_fma_f32 v[32:33], v[80:81], v[34:35], v[32:33]
	s_nop 0
	v_mul_f32_e32 v4, 0xbfb8aa3b, v32
	v_exp_f32_e32 v8, v4
	v_mov_b32_e32 v4, 1.0
	v_add_f32_e32 v8, 1.0, v8
	v_rcp_f32_e32 v34, v8
	v_mul_f32_e32 v8, 0xbfb8aa3b, v33
	v_exp_f32_e32 v8, v8
	s_nop 0
	v_add_f32_e32 v8, 1.0, v8
	v_rcp_f32_e32 v35, v8
	v_lshlrev_b32_e32 v8, 16, v9
	v_and_b32_e32 v9, 0xffff0000, v9
	v_pk_fma_f32 v[8:9], v[74:75], v[8:9], v[16:17]
	v_lshlrev_b32_e32 v16, 16, v21
	v_and_b32_e32 v17, 0xffff0000, v21
	v_pk_fma_f32 v[8:9], v[78:79], v[16:17], v[8:9]
	v_lshlrev_b32_e32 v16, 16, v5
	v_and_b32_e32 v17, 0xffff0000, v5
	v_pk_fma_f32 v[8:9], v[82:83], v[16:17], v[8:9]
	v_and_b32_e32 v21, 0xffff0000, v18
	v_mul_f32_e32 v5, 0xbfb8aa3b, v8
	v_exp_f32_e32 v5, v5
	v_pk_fma_f32 v[20:21], v[28:29], v[20:21], 0 op_sel_hi:[1,1,0]
	v_lshlrev_b32_e32 v28, 16, v10
	v_and_b32_e32 v29, 0xffff0000, v10
	v_add_f32_e32 v5, 1.0, v5
	v_rcp_f32_e32 v16, v5
	v_mul_f32_e32 v5, 0xbfb8aa3b, v9
	v_exp_f32_e32 v5, v5
	v_pk_fma_f32 v[20:21], v[24:25], v[28:29], v[20:21]
	v_lshlrev_b32_e32 v24, 16, v22
	v_and_b32_e32 v25, 0xffff0000, v22
	v_pk_fma_f32 v[12:13], v[12:13], v[24:25], v[20:21]
	v_lshlrev_b32_e32 v20, 16, v6
	v_and_b32_e32 v21, 0xffff0000, v6
	v_add_f32_e32 v5, 1.0, v5
	v_pk_fma_f32 v[0:1], v[0:1], v[20:21], v[12:13]
	v_rcp_f32_e32 v17, v5
	v_mul_f32_e32 v5, 0xbfb8aa3b, v0
	v_exp_f32_e32 v5, v5
	v_lshlrev_b32_e32 v18, 16, v19
	v_and_b32_e32 v19, 0xffff0000, v19
	v_pk_fma_f32 v[18:19], v[30:31], v[18:19], 0 op_sel_hi:[1,1,0]
	v_add_f32_e32 v5, 1.0, v5
	v_rcp_f32_e32 v12, v5
	v_mul_f32_e32 v5, 0xbfb8aa3b, v1
	v_exp_f32_e32 v5, v5
	v_lshlrev_b32_e32 v10, 16, v11
	v_and_b32_e32 v11, 0xffff0000, v11
	v_pk_fma_f32 v[10:11], v[26:27], v[10:11], v[18:19]
	v_lshlrev_b32_e32 v18, 16, v23
	v_and_b32_e32 v19, 0xffff0000, v23
	v_pk_fma_f32 v[10:11], v[14:15], v[18:19], v[10:11]
	v_lshlrev_b32_e32 v6, 16, v7
	v_and_b32_e32 v7, 0xffff0000, v7
	v_add_f32_e32 v5, 1.0, v5
	v_pk_fma_f32 v[2:3], v[2:3], v[6:7], v[10:11]
	v_rcp_f32_e32 v13, v5
	v_mul_f32_e32 v5, 0xbfb8aa3b, v2
	v_exp_f32_e32 v5, v5
	v_pk_mul_f32 v[32:33], v[32:33], v[34:35]
	v_pk_mul_f32 v[8:9], v[8:9], v[16:17]
	v_pk_mul_f32 v[34:35], v[32:33], v[32:33]
	v_add_f32_e32 v5, 1.0, v5
	v_rcp_f32_e32 v6, v5
	v_mul_f32_e32 v5, 0xbfb8aa3b, v3
	v_exp_f32_e32 v5, v5
	v_pk_mul_f32 v[16:17], v[8:9], v[8:9]
	v_pk_mul_f32 v[0:1], v[0:1], v[12:13]
	v_add_f32_e32 v5, 1.0, v5
	v_rcp_f32_e32 v7, v5
	v_add_f32_e32 v5, v34, v35
	v_add_f32_e32 v5, v16, v5
	v_pk_mul_f32 v[12:13], v[0:1], v[0:1]
	v_add_f32_e32 v5, v17, v5
	v_pk_mul_f32 v[2:3], v[2:3], v[6:7]
	v_add_f32_e32 v5, v12, v5
	v_pk_mul_f32 v[6:7], v[2:3], v[2:3]
	v_add_f32_e32 v5, v13, v5
	v_add_f32_e32 v5, v6, v5
	v_add_f32_e32 v5, v7, v5
	ds_bpermute_b32 v6, v37, v5
	s_waitcnt lgkmcnt(0)
	v_add_f32_e32 v5, v5, v6
	ds_bpermute_b32 v6, v38, v5
	s_waitcnt lgkmcnt(0)
	v_add_f32_e32 v5, v5, v6
	ds_bpermute_b32 v6, v39, v5
	s_waitcnt lgkmcnt(0)
	v_add_f32_e32 v5, v5, v6
	ds_bpermute_b32 v6, v40, v5
	s_and_saveexec_b64 s[22:23], vcc
	s_cbranch_execz .LBB0_754
	s_waitcnt lgkmcnt(0)
	v_add_f32_e32 v4, v5, v6
	v_add_f32_e32 v4, 0x358637bd, v4
	v_mul_f32_e32 v5, 0x4b800000, v4
	v_cmp_gt_f32_e32 vcc, s34, v4
	s_nop 1
	v_cndmask_b32_e32 v4, v4, v5, vcc
	v_rsq_f32_e32 v4, v4
	s_nop 0
	v_mul_f32_e32 v5, 0x45800000, v4
	v_cndmask_b32_e32 v4, v4, v5, vcc
	v_cmp_gt_u32_e32 vcc, s30, v41
	s_nop 1
	v_cndmask_b32_e32 v5, 1.0, v231, vcc
	v_mul_f32_e32 v4, v5, v4
.LBB0_754:
	s_or_b64 exec, exec, s[22:23]
	v_pk_mul_f32 v[0:1], v[0:1], v[4:5] op_sel_hi:[1,0]
	v_cmp_eq_u32_e32 vcc, 1, v43
	v_cvt_pk_bf16_f32 v12, v0, v1
	v_pk_mul_f32 v[0:1], v[2:3], v[4:5] op_sel_hi:[1,0]
	s_waitcnt lgkmcnt(0)
	v_pk_mul_f32 v[6:7], v[32:33], v[4:5] op_sel_hi:[1,0]
	v_cvt_pk_bf16_f32 v13, v0, v1
	v_cndmask_b32_e64 v0, v188, 0, vcc
	v_cmp_lt_u32_e32 vcc, s31, v41
	v_cvt_pk_bf16_f32 v10, v6, v7
	v_pk_mul_f32 v[6:7], v[8:9], v[4:5] op_sel_hi:[1,0]
	v_cndmask_b32_e32 v0, v232, v0, vcc
	v_add_u32_e32 v0, 0, v0
	v_mul_u32_u24_e32 v1, 0x110, v42
	v_cvt_pk_bf16_f32 v11, v6, v7
	v_add3_u32 v0, v0, v1, v151
	ds_write_b128 v0, v[10:13]
	v_add_u32_e32 v42, 0x200, v41
	v_add_u32_e32 v0, s87, v219
	v_lshrrev_b32_e32 v44, 10, v42
	v_and_b32_e32 v43, 63, v0
	v_lshl_add_u32 v1, v44, 9, v36
	v_add_u32_e32 v0, s86, v43
	v_mov_b32_e32 v8, 0
	v_cmp_lt_i32_e32 vcc, -1, v0
	v_lshlrev_b32_e32 v56, 1, v1
	v_mov_b32_e32 v16, 0
	v_mov_b32_e32 v17, 0
	v_mov_b32_e32 v18, 0
	v_mov_b32_e32 v19, 0
	s_and_saveexec_b64 s[22:23], vcc
	s_cbranch_execz .LBB0_756
	v_add_u32_e32 v1, s41, v0
	v_mad_u32_u24 v2, v1, s25, v56
	global_load_dwordx4 v[16:19], v2, s[10:11]

; #define LAS __attribute__((address_space(3)))
; __device__ __forceinline__ float lo_bf(unsigned w) { return __uint_as_float(w << 16); }
; __device__ __forceinline__ float hi_bf(unsigned w) { return __uint_as_float(w & 0xffff0000u); }
; __device__ __forceinline__ unsigned pk2(float lo, float hi) { const f32x2_t v = {lo, hi}; const bf16x2_t b = __builtin_convertvector(v, bf16x2_t); return __builtin_bit_cast(unsigned, b); }
; __device__ __forceinline__ float silu_(float x) { return x * sigm(x); }
; __device__ __forceinline__ void dn_prep_item(const Args& a, LAS unsigned char* lds, int item, int tid, int wave, int lane, int& cwh, int next_item) {
;     ...
;     for (int r = 0; r < 6; ++r) { const int task = tid + NTHR * r, which = task >> 10, i = (task & 1023) >> 4, gq = task & 15;
;         const int col = 1024 + which * 512 + h * 128 + 8 * gq;
;         v4u xv[4];
; #pragma unroll
;         for (int jj = 0; jj < 4; ++jj) { const int pos = n * 64 + i - 3 + jj; xv[jj] = (v4u){0u, 0u, 0u, 0u};
;             if (pos >= 0) xv[jj] = *(const v4u*)(P + (size_t)(b * T + pos) * NIN + col); }
;         float o[8];
; #pragma unroll
;         for (int q = 0; q < 8; ++q) o[q] = 0.f;
; #pragma unroll
;         for (int jj = 0; jj < 4; ++jj) { const v4u v = xv[jj];
;             const f32x4 w0 = *(const LAS f32x4*)(cwl + (which * 4 + jj) * 128 + 8 * gq), w1 = *(const LAS f32x4*)(cwl + (which * 4 + jj) * 128 + 8 * gq + 4);
;             o[0] += w0[0] * lo_bf(v.x); o[1] += w0[1] * hi_bf(v.x); o[2] += w0[2] * lo_bf(v.y); o[3] += w0[3] * hi_bf(v.y);
;             o[4] += w1[0] * lo_bf(v.z); o[5] += w1[1] * hi_bf(v.z); o[6] += w1[2] * lo_bf(v.w); o[7] += w1[3] * hi_bf(v.w); }
;         float s = 0.f;
; #pragma unroll
;         for (int q = 0; q < 8; ++q) { o[q] = silu_(o[q]); s += o[q] * o[q]; }
;         s += __shfl_xor(s, 1); s += __shfl_xor(s, 2); s += __shfl_xor(s, 4); s += __shfl_xor(s, 8);
;         const float inv = which == 2 ? 1.0f : rsqrtf(s + EPS) * (which == 0 ? 0.08838834764831845f : 1.0f);
;         v4u w; w.x = pk2(o[0] * inv, o[1] * inv); w.y = pk2(o[2] * inv, o[3] * inv); w.z = pk2(o[4] * inv, o[5] * inv); w.w = pk2(o[6] * inv, o[7] * inv);
;         *(LAS v4u*)(lds + (which == 0 ? L_QS : which == 1 ? L_KH : L_V) + i * KS_ + 16 * gq) = w;
.LBB0_760:
	s_or_b64 exec, exec, s[22:23]
	v_or_b32_e32 v2, s39, v43
	v_mad_u32_u24 v0, v2, s25, v56
	global_load_dwordx4 v[4:7], v0, s[10:11]
	v_lshl_add_u32 v0, v44, 11, v150
	ds_read_b128 v[72:75], v0
	ds_read_b128 v[28:31], v0 offset:16
	ds_read_b128 v[76:79], v0 offset:512
	ds_read_b128 v[24:27], v0 offset:528
	ds_read_b128 v[80:83], v0 offset:1024
	ds_read_b128 v[12:15], v0 offset:1040
	ds_read_b128 v[84:87], v0 offset:1536
	ds_read_b128 v[0:3], v0 offset:1552
	s_waitcnt vmcnt(1)
	v_lshlrev_b32_e32 v32, 16, v16
	v_and_b32_e32 v33, 0xffff0000, v16
	s_waitcnt lgkmcnt(7)
	v_pk_fma_f32 v[32:33], v[72:73], v[32:33], 0 op_sel_hi:[1,1,0]
	v_lshlrev_b32_e32 v34, 16, v8
	v_and_b32_e32 v35, 0xffff0000, v8
	s_waitcnt lgkmcnt(5)
	v_pk_fma_f32 v[32:33], v[76:77], v[34:35], v[32:33]
	v_lshlrev_b32_e32 v34, 16, v20
	v_and_b32_e32 v35, 0xffff0000, v20
	s_waitcnt lgkmcnt(3)
	v_pk_fma_f32 v[32:33], v[80:81], v[34:35], v[32:33]
	v_lshlrev_b32_e32 v16, 16, v17
	v_and_b32_e32 v17, 0xffff0000, v17
	v_pk_fma_f32 v[16:17], v[74:75], v[16:17], 0 op_sel_hi:[1,1,0]
	v_lshlrev_b32_e32 v20, 16, v18
	v_cmp_ne_u32_e32 vcc, 2, v44
	s_waitcnt vmcnt(0)
	v_lshlrev_b32_e32 v34, 16, v4
	v_and_b32_e32 v35, 0xffff0000, v4
	s_waitcnt lgkmcnt(1)
	v_pk_fma_f32 v[32:33], v[84:85], v[34:35], v[32:33]
	s_nop 0
	v_mul_f32_e32 v4, 0xbfb8aa3b, v32
	v_exp_f32_e32 v8, v4
	v_mov_b32_e32 v4, 1.0
	v_add_f32_e32 v8, 1.0, v8
	v_rcp_f32_e32 v34, v8
	v_mul_f32_e32 v8, 0xbfb8aa3b, v33
	v_exp_f32_e32 v8, v8
	s_nop 0
	v_add_f32_e32 v8, 1.0, v8
	v_rcp_f32_e32 v35, v8
	v_lshlrev_b32_e32 v8, 16, v9
	v_and_b32_e32 v9, 0xffff0000, v9
	v_pk_fma_f32 v[8:9], v[78:79], v[8:9], v[16:17]
	v_lshlrev_b32_e32 v16, 16, v21
	v_and_b32_e32 v17, 0xffff0000, v21
	v_pk_fma_f32 v[8:9], v[82:83], v[16:17], v[8:9]
	v_lshlrev_b32_e32 v16, 16, v5
	v_and_b32_e32 v17, 0xffff0000, v5
	v_pk_fma_f32 v[8:9], v[86:87], v[16:17], v[8:9]
	v_and_b32_e32 v21, 0xffff0000, v18
	v_mul_f32_e32 v5, 0xbfb8aa3b, v8
	v_exp_f32_e32 v5, v5
	v_pk_fma_f32 v[20:21], v[28:29], v[20:21], 0 op_sel_hi:[1,1,0]
	v_lshlrev_b32_e32 v28, 16, v10
	v_and_b32_e32 v29, 0xffff0000, v10
	v_add_f32_e32 v5, 1.0, v5
	v_rcp_f32_e32 v16, v5
	v_mul_f32_e32 v5, 0xbfb8aa3b, v9
	v_exp_f32_e32 v5, v5
	v_pk_fma_f32 v[20:21], v[24:25], v[28:29], v[20:21]
	v_lshlrev_b32_e32 v24, 16, v22
	v_and_b32_e32 v25, 0xffff0000, v22
	v_pk_fma_f32 v[12:13], v[12:13], v[24:25], v[20:21]
	v_lshlrev_b32_e32 v20, 16, v6
	v_and_b32_e32 v21, 0xffff0000, v6
	v_add_f32_e32 v5, 1.0, v5
	s_waitcnt lgkmcnt(0)
	v_pk_fma_f32 v[0:1], v[0:1], v[20:21], v[12:13]
	v_rcp_f32_e32 v17, v5
	v_mul_f32_e32 v5, 0xbfb8aa3b, v0
	v_exp_f32_e32 v5, v5
	v_lshlrev_b32_e32 v18, 16, v19
	v_and_b32_e32 v19, 0xffff0000, v19
	v_pk_fma_f32 v[18:19], v[30:31], v[18:19], 0 op_sel_hi:[1,1,0]
	v_add_f32_e32 v5, 1.0, v5
	v_rcp_f32_e32 v12, v5
	v_mul_f32_e32 v5, 0xbfb8aa3b, v1
	v_exp_f32_e32 v5, v5
	v_lshlrev_b32_e32 v10, 16, v11
	v_and_b32_e32 v11, 0xffff0000, v11
	v_pk_fma_f32 v[10:11], v[26:27], v[10:11], v[18:19]
	v_lshlrev_b32_e32 v18, 16, v23
	v_and_b32_e32 v19, 0xffff0000, v23
	v_pk_fma_f32 v[10:11], v[14:15], v[18:19], v[10:11]
	v_lshlrev_b32_e32 v6, 16, v7
	v_and_b32_e32 v7, 0xffff0000, v7
	v_add_f32_e32 v5, 1.0, v5
	v_pk_fma_f32 v[2:3], v[2:3], v[6:7], v[10:11]
	v_rcp_f32_e32 v13, v5
	v_mul_f32_e32 v5, 0xbfb8aa3b, v2
	v_exp_f32_e32 v5, v5
	v_pk_mul_f32 v[32:33], v[32:33], v[34:35]
	v_pk_mul_f32 v[8:9], v[8:9], v[16:17]
	v_pk_mul_f32 v[34:35], v[32:33], v[32:33]
	v_add_f32_e32 v5, 1.0, v5
	v_rcp_f32_e32 v6, v5
	v_mul_f32_e32 v5, 0xbfb8aa3b, v3
	v_exp_f32_e32 v5, v5
	v_pk_mul_f32 v[16:17], v[8:9], v[8:9]
	v_pk_mul_f32 v[0:1], v[0:1], v[12:13]
	v_add_f32_e32 v5, 1.0, v5
	v_rcp_f32_e32 v7, v5
	v_add_f32_e32 v5, v34, v35
	v_add_f32_e32 v5, v16, v5
	v_pk_mul_f32 v[12:13], v[0:1], v[0:1]
	v_add_f32_e32 v5, v17, v5
	v_pk_mul_f32 v[2:3], v[2:3], v[6:7]
	v_add_f32_e32 v5, v12, v5
	v_pk_mul_f32 v[6:7], v[2:3], v[2:3]
	v_add_f32_e32 v5, v13, v5
	v_add_f32_e32 v5, v6, v5
	v_add_f32_e32 v5, v7, v5
	ds_bpermute_b32 v6, v37, v5
	s_waitcnt lgkmcnt(0)
	v_add_f32_e32 v5, v5, v6
	ds_bpermute_b32 v6, v38, v5
	s_waitcnt lgkmcnt(0)
	v_add_f32_e32 v5, v5, v6
	ds_bpermute_b32 v6, v39, v5
	s_waitcnt lgkmcnt(0)
	v_add_f32_e32 v5, v5, v6
	ds_bpermute_b32 v6, v40, v5
	s_and_saveexec_b64 s[22:23], vcc
	s_cbranch_execz .LBB0_762
	s_waitcnt lgkmcnt(0)
	v_add_f32_e32 v4, v5, v6
	v_add_f32_e32 v4, 0x358637bd, v4
	v_mul_f32_e32 v5, 0x4b800000, v4
	v_cmp_gt_f32_e32 vcc, s34, v4
	s_nop 1
	v_cndmask_b32_e32 v4, v4, v5, vcc
	v_rsq_f32_e32 v4, v4
	s_nop 0
	v_mul_f32_e32 v5, 0x45800000, v4
	v_cndmask_b32_e32 v4, v4, v5, vcc
	v_cmp_gt_u32_e32 vcc, s30, v42
	s_nop 1
	v_cndmask_b32_e32 v5, 1.0, v231, vcc
	v_mul_f32_e32 v4, v5, v4
.LBB0_762:
	s_or_b64 exec, exec, s[22:23]
	v_pk_mul_f32 v[0:1], v[0:1], v[4:5] op_sel_hi:[1,0]
	v_cmp_eq_u32_e32 vcc, 1, v44
	v_cvt_pk_bf16_f32 v12, v0, v1
	v_pk_mul_f32 v[0:1], v[2:3], v[4:5] op_sel_hi:[1,0]
	s_waitcnt lgkmcnt(0)
	v_pk_mul_f32 v[6:7], v[32:33], v[4:5] op_sel_hi:[1,0]
	v_cvt_pk_bf16_f32 v13, v0, v1
	v_cndmask_b32_e64 v0, v188, 0, vcc
	v_cmp_lt_u32_e32 vcc, s31, v42
	v_cvt_pk_bf16_f32 v10, v6, v7
	v_pk_mul_f32 v[6:7], v[8:9], v[4:5] op_sel_hi:[1,0]
	v_cndmask_b32_e32 v0, v232, v0, vcc
	v_add_u32_e32 v0, 0, v0
	v_mul_u32_u24_e32 v1, 0x110, v43
	v_cvt_pk_bf16_f32 v11, v6, v7
	v_add3_u32 v0, v0, v1, v151
	ds_write_b128 v0, v[10:13]
	v_add_u32_e32 v0, 0x400, v41
	v_lshrrev_b32_e32 v43, 10, v0
	v_add_u32_e32 v0, s87, v218
	v_and_b32_e32 v42, 63, v0
	v_lshl_add_u32 v1, v43, 9, v36
	v_add_u32_e32 v0, s86, v42
	v_mov_b32_e32 v8, 0
	v_cmp_lt_i32_e32 vcc, -1, v0
	v_lshlrev_b32_e32 v56, 1, v1
	v_mov_b32_e32 v16, 0
	v_mov_b32_e32 v17, 0
	v_mov_b32_e32 v18, 0
	v_mov_b32_e32 v19, 0
	s_and_saveexec_b64 s[22:23], vcc
	s_cbranch_execz .LBB0_764
	v_add_u32_e32 v1, s41, v0
	v_mad_u32_u24 v2, v1, s25, v56
	global_load_dwordx4 v[16:19], v2, s[10:11]

; #define LAS __attribute__((address_space(3)))
; __device__ __forceinline__ float lo_bf(unsigned w) { return __uint_as_float(w << 16); }
; __device__ __forceinline__ float hi_bf(unsigned w) { return __uint_as_float(w & 0xffff0000u); }
; __device__ __forceinline__ unsigned pk2(float lo, float hi) { const f32x2_t v = {lo, hi}; const bf16x2_t b = __builtin_convertvector(v, bf16x2_t); return __builtin_bit_cast(unsigned, b); }
; __device__ __forceinline__ float silu_(float x) { return x * sigm(x); }
; __device__ __forceinline__ void dn_prep_item(const Args& a, LAS unsigned char* lds, int item, int tid, int wave, int lane, int& cwh, int next_item) {
;     ...
;     for (int r = 0; r < 6; ++r) { const int task = tid + NTHR * r, which = task >> 10, i = (task & 1023) >> 4, gq = task & 15;
;         const int col = 1024 + which * 512 + h * 128 + 8 * gq;
;         v4u xv[4];
; #pragma unroll
;         for (int jj = 0; jj < 4; ++jj) { const int pos = n * 64 + i - 3 + jj; xv[jj] = (v4u){0u, 0u, 0u, 0u};
;             if (pos >= 0) xv[jj] = *(const v4u*)(P + (size_t)(b * T + pos) * NIN + col); }
;         float o[8];
; #pragma unroll
;         for (int q = 0; q < 8; ++q) o[q] = 0.f;
; #pragma unroll
;         for (int jj = 0; jj < 4; ++jj) { const v4u v = xv[jj];
;             const f32x4 w0 = *(const LAS f32x4*)(cwl + (which * 4 + jj) * 128 + 8 * gq), w1 = *(const LAS f32x4*)(cwl + (which * 4 + jj) * 128 + 8 * gq + 4);
;             o[0] += w0[0] * lo_bf(v.x); o[1] += w0[1] * hi_bf(v.x); o[2] += w0[2] * lo_bf(v.y); o[3] += w0[3] * hi_bf(v.y);
;             o[4] += w1[0] * lo_bf(v.z); o[5] += w1[1] * hi_bf(v.z); o[6] += w1[2] * lo_bf(v.w); o[7] += w1[3] * hi_bf(v.w); }
;         float s = 0.f;
; #pragma unroll
;         for (int q = 0; q < 8; ++q) { o[q] = silu_(o[q]); s += o[q] * o[q]; }
;         s += __shfl_xor(s, 1); s += __shfl_xor(s, 2); s += __shfl_xor(s, 4); s += __shfl_xor(s, 8);
;         const float inv = which == 2 ? 1.0f : rsqrtf(s + EPS) * (which == 0 ? 0.08838834764831845f : 1.0f);
;         v4u w; w.x = pk2(o[0] * inv, o[1] * inv); w.y = pk2(o[2] * inv, o[3] * inv); w.z = pk2(o[4] * inv, o[5] * inv); w.w = pk2(o[6] * inv, o[7] * inv);
;         *(LAS v4u*)(lds + (which == 0 ? L_QS : which == 1 ? L_KH : L_V) + i * KS_ + 16 * gq) = w;
.LBB0_768:
	s_or_b64 exec, exec, s[22:23]
	v_or_b32_e32 v2, s39, v42
	v_mad_u32_u24 v0, v2, s25, v56
	global_load_dwordx4 v[4:7], v0, s[10:11]
	v_lshl_add_u32 v0, v43, 11, v150
	ds_read_b128 v[44:47], v0
	ds_read_b128 v[28:31], v0 offset:16
	ds_read_b128 v[72:75], v0 offset:512
	ds_read_b128 v[24:27], v0 offset:528
	ds_read_b128 v[76:79], v0 offset:1024
	ds_read_b128 v[12:15], v0 offset:1040
	ds_read_b128 v[80:83], v0 offset:1536
	ds_read_b128 v[0:3], v0 offset:1552
	s_waitcnt vmcnt(1)
	v_lshlrev_b32_e32 v32, 16, v16
	v_and_b32_e32 v33, 0xffff0000, v16
	s_waitcnt lgkmcnt(7)
	v_pk_fma_f32 v[32:33], v[44:45], v[32:33], 0 op_sel_hi:[1,1,0]
	v_lshlrev_b32_e32 v34, 16, v8
	v_and_b32_e32 v35, 0xffff0000, v8
	s_waitcnt lgkmcnt(5)
	v_pk_fma_f32 v[32:33], v[72:73], v[34:35], v[32:33]
	v_lshlrev_b32_e32 v34, 16, v20
	v_and_b32_e32 v35, 0xffff0000, v20
	s_waitcnt lgkmcnt(3)
	v_pk_fma_f32 v[32:33], v[76:77], v[34:35], v[32:33]
	v_lshlrev_b32_e32 v16, 16, v17
	v_and_b32_e32 v17, 0xffff0000, v17
	v_pk_fma_f32 v[16:17], v[46:47], v[16:17], 0 op_sel_hi:[1,1,0]
	v_lshlrev_b32_e32 v20, 16, v18
	v_cmp_ne_u32_e32 vcc, 2, v43
	s_waitcnt vmcnt(0)
	v_lshlrev_b32_e32 v34, 16, v4
	v_and_b32_e32 v35, 0xffff0000, v4
	s_waitcnt lgkmcnt(1)
	v_pk_fma_f32 v[32:33], v[80:81], v[34:35], v[32:33]
	s_nop 0
	v_mul_f32_e32 v4, 0xbfb8aa3b, v32
	v_exp_f32_e32 v8, v4
	v_mov_b32_e32 v4, 1.0
	v_add_f32_e32 v8, 1.0, v8
	v_rcp_f32_e32 v34, v8
	v_mul_f32_e32 v8, 0xbfb8aa3b, v33
	v_exp_f32_e32 v8, v8
	s_nop 0
	v_add_f32_e32 v8, 1.0, v8
	v_rcp_f32_e32 v35, v8
	v_lshlrev_b32_e32 v8, 16, v9
	v_and_b32_e32 v9, 0xffff0000, v9
	v_pk_fma_f32 v[8:9], v[74:75], v[8:9], v[16:17]
	v_lshlrev_b32_e32 v16, 16, v21
	v_and_b32_e32 v17, 0xffff0000, v21
	v_pk_fma_f32 v[8:9], v[78:79], v[16:17], v[8:9]
	v_lshlrev_b32_e32 v16, 16, v5
	v_and_b32_e32 v17, 0xffff0000, v5
	v_pk_fma_f32 v[8:9], v[82:83], v[16:17], v[8:9]
	v_and_b32_e32 v21, 0xffff0000, v18
	v_mul_f32_e32 v5, 0xbfb8aa3b, v8
	v_exp_f32_e32 v5, v5
	v_pk_fma_f32 v[20:21], v[28:29], v[20:21], 0 op_sel_hi:[1,1,0]
	v_lshlrev_b32_e32 v28, 16, v10
	v_and_b32_e32 v29, 0xffff0000, v10
	v_add_f32_e32 v5, 1.0, v5
	v_rcp_f32_e32 v16, v5
	v_mul_f32_e32 v5, 0xbfb8aa3b, v9
	v_exp_f32_e32 v5, v5
	v_pk_fma_f32 v[20:21], v[24:25], v[28:29], v[20:21]
	v_lshlrev_b32_e32 v24, 16, v22
	v_and_b32_e32 v25, 0xffff0000, v22
	v_pk_fma_f32 v[12:13], v[12:13], v[24:25], v[20:21]
	v_lshlrev_b32_e32 v20, 16, v6
	v_and_b32_e32 v21, 0xffff0000, v6
	v_add_f32_e32 v5, 1.0, v5
	s_waitcnt lgkmcnt(0)
	v_pk_fma_f32 v[0:1], v[0:1], v[20:21], v[12:13]
	v_rcp_f32_e32 v17, v5
	v_mul_f32_e32 v5, 0xbfb8aa3b, v0
	v_exp_f32_e32 v5, v5
	v_lshlrev_b32_e32 v18, 16, v19
	v_and_b32_e32 v19, 0xffff0000, v19
	v_pk_fma_f32 v[18:19], v[30:31], v[18:19], 0 op_sel_hi:[1,1,0]
	v_add_f32_e32 v5, 1.0, v5
	v_rcp_f32_e32 v12, v5
	v_mul_f32_e32 v5, 0xbfb8aa3b, v1
	v_exp_f32_e32 v5, v5
	v_lshlrev_b32_e32 v10, 16, v11
	v_and_b32_e32 v11, 0xffff0000, v11
	v_pk_fma_f32 v[10:11], v[26:27], v[10:11], v[18:19]
	v_lshlrev_b32_e32 v18, 16, v23
	v_and_b32_e32 v19, 0xffff0000, v23
	v_pk_fma_f32 v[10:11], v[14:15], v[18:19], v[10:11]
	v_lshlrev_b32_e32 v6, 16, v7
	v_and_b32_e32 v7, 0xffff0000, v7
	v_add_f32_e32 v5, 1.0, v5
	v_pk_fma_f32 v[2:3], v[2:3], v[6:7], v[10:11]
	v_rcp_f32_e32 v13, v5
	v_mul_f32_e32 v5, 0xbfb8aa3b, v2
	v_exp_f32_e32 v5, v5
	v_pk_mul_f32 v[32:33], v[32:33], v[34:35]
	v_pk_mul_f32 v[8:9], v[8:9], v[16:17]
	v_pk_mul_f32 v[34:35], v[32:33], v[32:33]
	v_add_f32_e32 v5, 1.0, v5
	v_rcp_f32_e32 v6, v5
	v_mul_f32_e32 v5, 0xbfb8aa3b, v3
	v_exp_f32_e32 v5, v5
	v_pk_mul_f32 v[16:17], v[8:9], v[8:9]
	v_pk_mul_f32 v[0:1], v[0:1], v[12:13]
	v_add_f32_e32 v5, 1.0, v5
	v_rcp_f32_e32 v7, v5
	v_add_f32_e32 v5, v34, v35
	v_add_f32_e32 v5, v16, v5
	v_pk_mul_f32 v[12:13], v[0:1], v[0:1]
	v_add_f32_e32 v5, v17, v5
	v_pk_mul_f32 v[2:3], v[2:3], v[6:7]
	v_add_f32_e32 v5, v12, v5
	v_pk_mul_f32 v[6:7], v[2:3], v[2:3]
	v_add_f32_e32 v5, v13, v5
	v_add_f32_e32 v5, v6, v5
	v_add_f32_e32 v5, v7, v5
	ds_bpermute_b32 v6, v37, v5
	s_waitcnt lgkmcnt(0)
	v_add_f32_e32 v5, v5, v6
	ds_bpermute_b32 v6, v38, v5
	s_waitcnt lgkmcnt(0)
	v_add_f32_e32 v5, v5, v6
	ds_bpermute_b32 v6, v39, v5
	s_waitcnt lgkmcnt(0)
	v_add_f32_e32 v5, v5, v6
	ds_bpermute_b32 v6, v40, v5
	s_and_saveexec_b64 s[22:23], vcc
	s_cbranch_execz .LBB0_745
	s_waitcnt lgkmcnt(0)
	v_add_f32_e32 v4, v5, v6
	v_add_f32_e32 v4, 0x358637bd, v4
	v_mul_f32_e32 v5, 0x4b800000, v4
	v_cmp_gt_f32_e32 vcc, s34, v4
	s_nop 1
	v_cndmask_b32_e32 v4, v4, v5, vcc
	v_rsq_f32_e32 v4, v4
	s_nop 0
	v_mul_f32_e32 v5, 0x45800000, v4
	v_cndmask_b32_e32 v4, v4, v5, vcc
	s_branch .LBB0_745
